# tight polling: no s_sleep in the grid-barrier and panel-exchange spin loops
# speedup vs baseline: 1.0072x; 1.0072x over previous
.LBB0_16:
	global_load_dword v3, v1, s[4:5] offset:32 sc1
	s_waitcnt vmcnt(0)
	v_and_b32_e32 v3, 0xffff0000, v3
	v_cmp_ne_u32_e32 vcc, v3, v2
	s_or_b64 s[6:7], vcc, s[6:7]
	s_andn2_b64 exec, exec, s[6:7]
	s_cbranch_execnz .LBB0_16

.LBB0_90:
	global_load_dword v16, v17, s[8:9] sc1
	global_load_dword v1, v17, s[10:11] sc1
	global_load_dword v2, v17, s[12:13] sc1
	global_load_dword v3, v17, s[14:15] sc1
	global_load_dword v4, v17, s[16:17] sc1
	global_load_dword v5, v17, s[22:23] sc1
	global_load_dword v6, v17, s[24:25] sc1
	global_load_dword v7, v17, s[28:29] sc1
	global_load_dword v8, v17, s[30:31] sc1
	global_load_dword v9, v17, s[38:39] sc1
	global_load_dword v10, v17, s[42:43] sc1
	global_load_dword v11, v17, s[44:45] sc1
	global_load_dword v12, v17, s[46:47] sc1
	global_load_dword v13, v17, s[62:63] sc1
	global_load_dword v14, v17, s[64:65] sc1
	global_load_dword v15, v17, s[66:67] sc1
	s_mov_b64 s[68:69], -1
	s_mov_b64 s[70:71], -1
	s_waitcnt vmcnt(14)
	v_add_u32_e32 v18, v1, v16
	s_waitcnt vmcnt(13)
	v_add_u32_e32 v18, v18, v2
	s_waitcnt vmcnt(12)
	v_add_u32_e32 v18, v18, v3
	s_waitcnt vmcnt(11)
	v_add_u32_e32 v18, v18, v4
	s_waitcnt vmcnt(10)
	v_add_u32_e32 v18, v18, v5
	s_waitcnt vmcnt(9)
	v_add_u32_e32 v18, v18, v6
	s_waitcnt vmcnt(8)
	v_add_u32_e32 v18, v18, v7
	s_waitcnt vmcnt(7)
	v_add_u32_e32 v18, v18, v8
	s_waitcnt vmcnt(6)
	v_add_u32_e32 v18, v18, v9
	s_waitcnt vmcnt(5)
	v_add_u32_e32 v18, v18, v10
	s_waitcnt vmcnt(4)
	v_add_u32_e32 v18, v18, v11
	s_waitcnt vmcnt(3)
	v_add_u32_e32 v18, v18, v12
	s_waitcnt vmcnt(2)
	v_add_u32_e32 v18, v18, v13
	s_waitcnt vmcnt(1)
	v_add_u32_e32 v18, v18, v14
	s_waitcnt vmcnt(0)
	v_add_u32_e32 v18, v18, v15
	v_cmp_eq_u32_e32 vcc, s3, v18
	s_cbranch_vccnz .LBB0_89
	s_and_b32 s61, s60, 0xff
	s_cmp_eq_u32 s61, 0
	s_mov_b64 s[72:73], -1
	s_cbranch_scc0 .LBB0_94
	global_load_dword v18, v17, s[6:7] sc1
	s_waitcnt vmcnt(0)
	v_cmp_eq_u32_e32 vcc, 0, v18
	s_cbranch_vccnz .LBB0_96
	s_mov_b64 s[72:73], 0

.LBB0_106:
	s_and_b32 s28, s3, 0xff
	s_mov_b64 s[24:25], -1
	s_cmp_lg_u32 s28, 0
	s_mov_b64 s[30:31], -1
	s_cbranch_scc1 .LBB0_109
	global_load_dword v3, v1, s[12:13] sc1
	s_waitcnt vmcnt(0)
	v_cmp_eq_u32_e32 vcc, 0, v3
	s_cbranch_vccnz .LBB0_111
	s_mov_b64 s[30:31], 0
	s_mov_b64 s[28:29], -1

.LBB0_123:
	s_and_b32 s24, s3, 0xff
	s_cmp_lg_u32 s24, 0
	s_mov_b64 s[28:29], -1
	s_cbranch_scc1 .LBB0_126
	global_load_dword v2, v1, s[12:13] sc1
	s_waitcnt vmcnt(0)
	v_cmp_eq_u32_e32 vcc, 0, v2
	s_cbranch_vccnz .LBB0_128
	s_mov_b64 s[28:29], 0
	s_mov_b64 s[24:25], -1

.LBB0_174:
	global_load_dword v16, v17, s[8:9] sc1
	global_load_dword v1, v17, s[10:11] sc1
	global_load_dword v2, v17, s[12:13] sc1
	global_load_dword v3, v17, s[14:15] sc1
	global_load_dword v4, v17, s[16:17] sc1
	global_load_dword v5, v17, s[24:25] sc1
	global_load_dword v6, v17, s[28:29] sc1
	global_load_dword v7, v17, s[30:31] sc1
	global_load_dword v8, v17, s[38:39] sc1
	global_load_dword v9, v17, s[40:41] sc1
	global_load_dword v10, v17, s[42:43] sc1
	global_load_dword v11, v17, s[44:45] sc1
	global_load_dword v12, v17, s[46:47] sc1
	global_load_dword v13, v17, s[62:63] sc1
	global_load_dword v14, v17, s[64:65] sc1
	global_load_dword v15, v17, s[66:67] sc1
	s_mov_b64 s[68:69], -1
	s_mov_b64 s[70:71], -1
	s_waitcnt vmcnt(14)
	v_add_u32_e32 v18, v1, v16
	s_waitcnt vmcnt(13)
	v_add_u32_e32 v18, v18, v2
	s_waitcnt vmcnt(12)
	v_add_u32_e32 v18, v18, v3
	s_waitcnt vmcnt(11)
	v_add_u32_e32 v18, v18, v4
	s_waitcnt vmcnt(10)
	v_add_u32_e32 v18, v18, v5
	s_waitcnt vmcnt(9)
	v_add_u32_e32 v18, v18, v6
	s_waitcnt vmcnt(8)
	v_add_u32_e32 v18, v18, v7
	s_waitcnt vmcnt(7)
	v_add_u32_e32 v18, v18, v8
	s_waitcnt vmcnt(6)
	v_add_u32_e32 v18, v18, v9
	s_waitcnt vmcnt(5)
	v_add_u32_e32 v18, v18, v10
	s_waitcnt vmcnt(4)
	v_add_u32_e32 v18, v18, v11
	s_waitcnt vmcnt(3)
	v_add_u32_e32 v18, v18, v12
	s_waitcnt vmcnt(2)
	v_add_u32_e32 v18, v18, v13
	s_waitcnt vmcnt(1)
	v_add_u32_e32 v18, v18, v14
	s_waitcnt vmcnt(0)
	v_add_u32_e32 v18, v18, v15
	v_cmp_eq_u32_e32 vcc, s3, v18
	s_cbranch_vccnz .LBB0_173
	s_and_b32 s61, s60, 0xff
	s_cmp_eq_u32 s61, 0
	s_mov_b64 s[72:73], -1
	s_cbranch_scc0 .LBB0_178
	global_load_dword v18, v17, s[6:7] sc1
	s_waitcnt vmcnt(0)
	v_cmp_eq_u32_e32 vcc, 0, v18
	s_cbranch_vccnz .LBB0_180
	s_mov_b64 s[72:73], 0

.LBB0_190:
	s_and_b32 s30, s3, 0xff
	s_mov_b64 s[28:29], -1
	s_cmp_lg_u32 s30, 0
	s_mov_b64 s[38:39], -1
	s_cbranch_scc1 .LBB0_193
	global_load_dword v3, v1, s[12:13] sc1
	s_waitcnt vmcnt(0)
	v_cmp_eq_u32_e32 vcc, 0, v3
	s_cbranch_vccnz .LBB0_195
	s_mov_b64 s[38:39], 0
	s_mov_b64 s[30:31], -1

.LBB0_207:
	s_and_b32 s28, s3, 0xff
	s_cmp_lg_u32 s28, 0
	s_mov_b64 s[30:31], -1
	s_cbranch_scc1 .LBB0_210
	global_load_dword v2, v1, s[12:13] sc1
	s_waitcnt vmcnt(0)
	v_cmp_eq_u32_e32 vcc, 0, v2
	s_cbranch_vccnz .LBB0_212
	s_mov_b64 s[30:31], 0
	s_mov_b64 s[28:29], -1

.LBB0_428:
	global_load_dword v16, v17, s[8:9] sc1
	global_load_dword v1, v17, s[10:11] sc1
	global_load_dword v2, v17, s[12:13] sc1
	global_load_dword v3, v17, s[14:15] sc1
	global_load_dword v4, v17, s[16:17] sc1
	global_load_dword v5, v17, s[18:19] sc1
	global_load_dword v6, v17, s[20:21] sc1
	global_load_dword v7, v17, s[24:25] sc1
	global_load_dword v8, v17, s[28:29] sc1
	global_load_dword v9, v17, s[30:31] sc1
	global_load_dword v10, v17, s[38:39] sc1
	global_load_dword v11, v17, s[40:41] sc1
	global_load_dword v12, v17, s[42:43] sc1
	global_load_dword v13, v17, s[44:45] sc1
	global_load_dword v14, v17, s[46:47] sc1
	global_load_dword v15, v17, s[62:63] sc1
	s_mov_b64 s[64:65], -1
	s_mov_b64 s[66:67], -1
	s_waitcnt vmcnt(14)
	v_add_u32_e32 v18, v1, v16
	s_waitcnt vmcnt(13)
	v_add_u32_e32 v18, v18, v2
	s_waitcnt vmcnt(12)
	v_add_u32_e32 v18, v18, v3
	s_waitcnt vmcnt(11)
	v_add_u32_e32 v18, v18, v4
	s_waitcnt vmcnt(10)
	v_add_u32_e32 v18, v18, v5
	s_waitcnt vmcnt(9)
	v_add_u32_e32 v18, v18, v6
	s_waitcnt vmcnt(8)
	v_add_u32_e32 v18, v18, v7
	s_waitcnt vmcnt(7)
	v_add_u32_e32 v18, v18, v8
	s_waitcnt vmcnt(6)
	v_add_u32_e32 v18, v18, v9
	s_waitcnt vmcnt(5)
	v_add_u32_e32 v18, v18, v10
	s_waitcnt vmcnt(4)
	v_add_u32_e32 v18, v18, v11
	s_waitcnt vmcnt(3)
	v_add_u32_e32 v18, v18, v12
	s_waitcnt vmcnt(2)
	v_add_u32_e32 v18, v18, v13
	s_waitcnt vmcnt(1)
	v_add_u32_e32 v18, v18, v14
	s_waitcnt vmcnt(0)
	v_add_u32_e32 v18, v18, v15
	v_cmp_eq_u32_e32 vcc, s3, v18
	s_cbranch_vccnz .LBB0_427
	s_and_b32 s61, s60, 0xff
	s_cmp_eq_u32 s61, 0
	s_mov_b64 s[68:69], -1
	s_cbranch_scc0 .LBB0_432
	global_load_dword v18, v17, s[6:7] sc1
	s_waitcnt vmcnt(0)
	v_cmp_eq_u32_e32 vcc, 0, v18
	s_cbranch_vccnz .LBB0_434
	s_mov_b64 s[68:69], 0

.LBB0_444:
	s_and_b32 s24, s3, 0xff
	s_mov_b64 s[20:21], -1
	s_cmp_lg_u32 s24, 0
	s_mov_b64 s[28:29], -1
	s_cbranch_scc1 .LBB0_447
	global_load_dword v3, v1, s[12:13] sc1
	s_waitcnt vmcnt(0)
	v_cmp_eq_u32_e32 vcc, 0, v3
	s_cbranch_vccnz .LBB0_449
	s_mov_b64 s[28:29], 0
	s_mov_b64 s[24:25], -1

.LBB0_461:
	s_and_b32 s20, s3, 0xff
	s_cmp_lg_u32 s20, 0
	s_mov_b64 s[24:25], -1
	s_cbranch_scc1 .LBB0_464
	global_load_dword v2, v1, s[12:13] sc1
	s_waitcnt vmcnt(0)
	v_cmp_eq_u32_e32 vcc, 0, v2
	s_cbranch_vccnz .LBB0_466
	s_mov_b64 s[24:25], 0
	s_mov_b64 s[20:21], -1

.LBB0_521:
	global_load_dword v16, v17, s[8:9] sc1
	global_load_dword v1, v17, s[10:11] sc1
	global_load_dword v2, v17, s[12:13] sc1
	global_load_dword v3, v17, s[14:15] sc1
	global_load_dword v4, v17, s[16:17] sc1
	global_load_dword v5, v17, s[18:19] sc1
	global_load_dword v6, v17, s[24:25] sc1
	global_load_dword v7, v17, s[28:29] sc1
	global_load_dword v8, v17, s[30:31] sc1
	global_load_dword v9, v17, s[36:37] sc1
	global_load_dword v10, v17, s[38:39] sc1
	global_load_dword v11, v17, s[40:41] sc1
	global_load_dword v12, v17, s[42:43] sc1
	global_load_dword v13, v17, s[44:45] sc1
	global_load_dword v14, v17, s[46:47] sc1
	global_load_dword v15, v17, s[62:63] sc1
	s_mov_b64 s[64:65], -1
	s_mov_b64 s[66:67], -1
	s_waitcnt vmcnt(14)
	v_add_u32_e32 v18, v1, v16
	s_waitcnt vmcnt(13)
	v_add_u32_e32 v18, v18, v2
	s_waitcnt vmcnt(12)
	v_add_u32_e32 v18, v18, v3
	s_waitcnt vmcnt(11)
	v_add_u32_e32 v18, v18, v4
	s_waitcnt vmcnt(10)
	v_add_u32_e32 v18, v18, v5
	s_waitcnt vmcnt(9)
	v_add_u32_e32 v18, v18, v6
	s_waitcnt vmcnt(8)
	v_add_u32_e32 v18, v18, v7
	s_waitcnt vmcnt(7)
	v_add_u32_e32 v18, v18, v8
	s_waitcnt vmcnt(6)
	v_add_u32_e32 v18, v18, v9
	s_waitcnt vmcnt(5)
	v_add_u32_e32 v18, v18, v10
	s_waitcnt vmcnt(4)
	v_add_u32_e32 v18, v18, v11
	s_waitcnt vmcnt(3)
	v_add_u32_e32 v18, v18, v12
	s_waitcnt vmcnt(2)
	v_add_u32_e32 v18, v18, v13
	s_waitcnt vmcnt(1)
	v_add_u32_e32 v18, v18, v14
	s_waitcnt vmcnt(0)
	v_add_u32_e32 v18, v18, v15
	v_cmp_eq_u32_e32 vcc, s3, v18
	s_cbranch_vccnz .LBB0_520
	s_and_b32 s61, s60, 0xff
	s_cmp_eq_u32 s61, 0
	s_mov_b64 s[68:69], -1
	s_cbranch_scc0 .LBB0_525
	global_load_dword v18, v17, s[6:7] sc1
	s_waitcnt vmcnt(0)
	v_cmp_eq_u32_e32 vcc, 0, v18
	s_cbranch_vccnz .LBB0_527
	s_mov_b64 s[68:69], 0

.LBB0_596:
	global_load_dword v17, v18, s[6:7] sc1
	global_load_dword v2, v18, s[8:9] sc1
	global_load_dword v3, v18, s[10:11] sc1
	global_load_dword v4, v18, s[12:13] sc1
	global_load_dword v5, v18, s[14:15] sc1
	global_load_dword v6, v18, s[16:17] sc1
	global_load_dword v7, v18, s[18:19] sc1
	global_load_dword v8, v18, s[24:25] sc1
	global_load_dword v9, v18, s[28:29] sc1
	global_load_dword v10, v18, s[30:31] sc1
	global_load_dword v11, v18, s[36:37] sc1
	global_load_dword v12, v18, s[38:39] sc1
	global_load_dword v13, v18, s[40:41] sc1
	global_load_dword v14, v18, s[42:43] sc1
	global_load_dword v15, v18, s[44:45] sc1
	global_load_dword v16, v18, s[46:47] sc1
	s_mov_b64 s[62:63], -1
	s_mov_b64 s[64:65], -1
	s_waitcnt vmcnt(14)
	v_add_u32_e32 v19, v2, v17
	s_waitcnt vmcnt(13)
	v_add_u32_e32 v19, v19, v3
	s_waitcnt vmcnt(12)
	v_add_u32_e32 v19, v19, v4
	s_waitcnt vmcnt(11)
	v_add_u32_e32 v19, v19, v5
	s_waitcnt vmcnt(10)
	v_add_u32_e32 v19, v19, v6
	s_waitcnt vmcnt(9)
	v_add_u32_e32 v19, v19, v7
	s_waitcnt vmcnt(8)
	v_add_u32_e32 v19, v19, v8
	s_waitcnt vmcnt(7)
	v_add_u32_e32 v19, v19, v9
	s_waitcnt vmcnt(6)
	v_add_u32_e32 v19, v19, v10
	s_waitcnt vmcnt(5)
	v_add_u32_e32 v19, v19, v11
	s_waitcnt vmcnt(4)
	v_add_u32_e32 v19, v19, v12
	s_waitcnt vmcnt(3)
	v_add_u32_e32 v19, v19, v13
	s_waitcnt vmcnt(2)
	v_add_u32_e32 v19, v19, v14
	s_waitcnt vmcnt(1)
	v_add_u32_e32 v19, v19, v15
	s_waitcnt vmcnt(0)
	v_add_u32_e32 v19, v19, v16
	v_cmp_eq_u32_e32 vcc, s3, v19
	s_cbranch_vccnz .LBB0_595
	s_and_b32 s61, s60, 0xff
	s_cmp_eq_u32 s61, 0
	s_mov_b64 s[66:67], -1
	s_cbranch_scc0 .LBB0_600
	global_load_dword v19, v18, s[4:5] sc1
	s_waitcnt vmcnt(0)
	v_cmp_eq_u32_e32 vcc, 0, v19
	s_cbranch_vccnz .LBB0_602
	s_mov_b64 s[66:67], 0

.LBB0_612:
	s_and_b32 s24, s3, 0xff
	s_mov_b64 s[18:19], -1
	s_cmp_lg_u32 s24, 0
	s_mov_b64 s[28:29], -1
	s_cbranch_scc1 .LBB0_615
	global_load_dword v4, v2, s[10:11] sc1
	s_waitcnt vmcnt(0)
	v_cmp_eq_u32_e32 vcc, 0, v4
	s_cbranch_vccnz .LBB0_617
	s_mov_b64 s[28:29], 0
	s_mov_b64 s[24:25], -1

.LBB0_629:
	s_and_b32 s18, s3, 0xff
	s_cmp_lg_u32 s18, 0
	s_mov_b64 s[24:25], -1
	s_cbranch_scc1 .LBB0_632
	global_load_dword v3, v2, s[10:11] sc1
	s_waitcnt vmcnt(0)
	v_cmp_eq_u32_e32 vcc, 0, v3
	s_cbranch_vccnz .LBB0_634
	s_mov_b64 s[24:25], 0
	s_mov_b64 s[18:19], -1

.LBB0_773:
	global_load_dword v17, v18, s[8:9] sc1
	global_load_dword v2, v18, s[10:11] sc1
	global_load_dword v3, v18, s[12:13] sc1
	global_load_dword v4, v18, s[14:15] sc1
	global_load_dword v5, v18, s[16:17] sc1
	global_load_dword v6, v18, s[18:19] sc1
	global_load_dword v7, v18, s[24:25] sc1
	global_load_dword v8, v18, s[28:29] sc1
	global_load_dword v9, v18, s[30:31] sc1
	global_load_dword v10, v18, s[36:37] sc1
	global_load_dword v11, v18, s[38:39] sc1
	global_load_dword v12, v18, s[40:41] sc1
	global_load_dword v13, v18, s[42:43] sc1
	global_load_dword v14, v18, s[44:45] sc1
	global_load_dword v15, v18, s[46:47] sc1
	global_load_dword v16, v18, s[48:49] sc1
	s_mov_b64 s[62:63], -1
	s_mov_b64 s[64:65], -1
	s_waitcnt vmcnt(14)
	v_add_u32_e32 v19, v2, v17
	s_waitcnt vmcnt(13)
	v_add_u32_e32 v19, v19, v3
	s_waitcnt vmcnt(12)
	v_add_u32_e32 v19, v19, v4
	s_waitcnt vmcnt(11)
	v_add_u32_e32 v19, v19, v5
	s_waitcnt vmcnt(10)
	v_add_u32_e32 v19, v19, v6
	s_waitcnt vmcnt(9)
	v_add_u32_e32 v19, v19, v7
	s_waitcnt vmcnt(8)
	v_add_u32_e32 v19, v19, v8
	s_waitcnt vmcnt(7)
	v_add_u32_e32 v19, v19, v9
	s_waitcnt vmcnt(6)
	v_add_u32_e32 v19, v19, v10
	s_waitcnt vmcnt(5)
	v_add_u32_e32 v19, v19, v11
	s_waitcnt vmcnt(4)
	v_add_u32_e32 v19, v19, v12
	s_waitcnt vmcnt(3)
	v_add_u32_e32 v19, v19, v13
	s_waitcnt vmcnt(2)
	v_add_u32_e32 v19, v19, v14
	s_waitcnt vmcnt(1)
	v_add_u32_e32 v19, v19, v15
	s_waitcnt vmcnt(0)
	v_add_u32_e32 v19, v19, v16
	v_cmp_eq_u32_e32 vcc, s3, v19
	s_cbranch_vccnz .LBB0_772
	s_and_b32 s61, s60, 0xff
	s_cmp_eq_u32 s61, 0
	s_mov_b64 s[66:67], -1
	s_cbranch_scc0 .LBB0_777
	global_load_dword v19, v18, s[6:7] sc1
	s_waitcnt vmcnt(0)
	v_cmp_eq_u32_e32 vcc, 0, v19
	s_cbranch_vccnz .LBB0_779
	s_mov_b64 s[66:67], 0

.LBB0_789:
	s_and_b32 s28, s3, 0xff
	s_mov_b64 s[24:25], -1
	s_cmp_lg_u32 s28, 0
	s_mov_b64 s[30:31], -1
	s_cbranch_scc1 .LBB0_792
	global_load_dword v4, v2, s[12:13] sc1
	s_waitcnt vmcnt(0)
	v_cmp_eq_u32_e32 vcc, 0, v4
	s_cbranch_vccnz .LBB0_794
	s_mov_b64 s[30:31], 0
	s_mov_b64 s[28:29], -1

.LBB0_806:
	s_and_b32 s24, s3, 0xff
	s_cmp_lg_u32 s24, 0
	s_mov_b64 s[28:29], -1
	s_cbranch_scc1 .LBB0_809
	global_load_dword v3, v2, s[12:13] sc1
	s_waitcnt vmcnt(0)
	v_cmp_eq_u32_e32 vcc, 0, v3
	s_cbranch_vccnz .LBB0_811
	s_mov_b64 s[28:29], 0
	s_mov_b64 s[24:25], -1

.LBB0_1024:
	global_load_dword v17, v18, s[8:9] sc1
	global_load_dword v2, v18, s[10:11] sc1
	global_load_dword v3, v18, s[12:13] sc1
	global_load_dword v4, v18, s[14:15] sc1
	global_load_dword v5, v18, s[16:17] sc1
	global_load_dword v6, v18, s[18:19] sc1
	global_load_dword v7, v18, s[22:23] sc1
	global_load_dword v8, v18, s[24:25] sc1
	global_load_dword v9, v18, s[26:27] sc1
	global_load_dword v10, v18, s[28:29] sc1
	global_load_dword v11, v18, s[30:31] sc1
	global_load_dword v12, v18, s[36:37] sc1
	global_load_dword v13, v18, s[38:39] sc1
	global_load_dword v14, v18, s[40:41] sc1
	global_load_dword v15, v18, s[42:43] sc1
	global_load_dword v16, v18, s[44:45] sc1
	s_mov_b64 s[46:47], -1
	s_mov_b64 s[48:49], -1
	s_waitcnt vmcnt(14)
	v_add_u32_e32 v19, v2, v17
	s_waitcnt vmcnt(13)
	v_add_u32_e32 v19, v19, v3
	s_waitcnt vmcnt(12)
	v_add_u32_e32 v19, v19, v4
	s_waitcnt vmcnt(11)
	v_add_u32_e32 v19, v19, v5
	s_waitcnt vmcnt(10)
	v_add_u32_e32 v19, v19, v6
	s_waitcnt vmcnt(9)
	v_add_u32_e32 v19, v19, v7
	s_waitcnt vmcnt(8)
	v_add_u32_e32 v19, v19, v8
	s_waitcnt vmcnt(7)
	v_add_u32_e32 v19, v19, v9
	s_waitcnt vmcnt(6)
	v_add_u32_e32 v19, v19, v10
	s_waitcnt vmcnt(5)
	v_add_u32_e32 v19, v19, v11
	s_waitcnt vmcnt(4)
	v_add_u32_e32 v19, v19, v12
	s_waitcnt vmcnt(3)
	v_add_u32_e32 v19, v19, v13
	s_waitcnt vmcnt(2)
	v_add_u32_e32 v19, v19, v14
	s_waitcnt vmcnt(1)
	v_add_u32_e32 v19, v19, v15
	s_waitcnt vmcnt(0)
	v_add_u32_e32 v19, v19, v16
	v_cmp_eq_u32_e32 vcc, s3, v19
	s_cbranch_vccnz .LBB0_1023
	s_and_b32 s46, s60, 0xff
	s_cmp_eq_u32 s46, 0
	s_mov_b64 s[46:47], -1
	s_mov_b64 s[50:51], -1
	s_cbranch_scc0 .LBB0_1028
	global_load_dword v19, v18, s[6:7] sc1
	s_waitcnt vmcnt(0)
	v_cmp_eq_u32_e32 vcc, 0, v19
	s_cbranch_vccnz .LBB0_1030
	s_mov_b64 s[50:51], 0

.LBB0_1040:
	s_and_b32 s24, s3, 0xff
	s_mov_b64 s[22:23], -1
	s_cmp_lg_u32 s24, 0
	s_mov_b64 s[26:27], -1
	s_cbranch_scc1 .LBB0_1043
	global_load_dword v4, v2, s[12:13] sc1
	s_waitcnt vmcnt(0)
	v_cmp_eq_u32_e32 vcc, 0, v4
	s_cbranch_vccnz .LBB0_1045
	s_mov_b64 s[26:27], 0
	s_mov_b64 s[24:25], -1

.LBB0_1057:
	s_and_b32 s22, s3, 0xff
	s_cmp_lg_u32 s22, 0
	s_mov_b64 s[24:25], -1
	s_cbranch_scc1 .LBB0_1060
	global_load_dword v3, v2, s[12:13] sc1
	s_waitcnt vmcnt(0)
	v_cmp_eq_u32_e32 vcc, 0, v3
	s_cbranch_vccnz .LBB0_1062
	s_mov_b64 s[24:25], 0
	s_mov_b64 s[22:23], -1

.LBB0_1099:
	global_load_dword v16, v17, s[6:7] sc1
	global_load_dword v1, v17, s[8:9] sc1
	global_load_dword v2, v17, s[10:11] sc1
	global_load_dword v3, v17, s[12:13] sc1
	global_load_dword v4, v17, s[14:15] sc1
	global_load_dword v5, v17, s[16:17] sc1
	global_load_dword v6, v17, s[18:19] sc1
	global_load_dword v7, v17, s[22:23] sc1
	global_load_dword v8, v17, s[24:25] sc1
	global_load_dword v9, v17, s[26:27] sc1
	global_load_dword v10, v17, s[28:29] sc1
	global_load_dword v11, v17, s[30:31] sc1
	global_load_dword v12, v17, s[36:37] sc1
	global_load_dword v13, v17, s[38:39] sc1
	global_load_dword v14, v17, s[40:41] sc1
	global_load_dword v15, v17, s[42:43] sc1
	s_mov_b64 s[44:45], -1
	s_mov_b64 s[46:47], -1
	s_waitcnt vmcnt(14)
	v_add_u32_e32 v18, v1, v16
	s_waitcnt vmcnt(13)
	v_add_u32_e32 v18, v18, v2
	s_waitcnt vmcnt(12)
	v_add_u32_e32 v18, v18, v3
	s_waitcnt vmcnt(11)
	v_add_u32_e32 v18, v18, v4
	s_waitcnt vmcnt(10)
	v_add_u32_e32 v18, v18, v5
	s_waitcnt vmcnt(9)
	v_add_u32_e32 v18, v18, v6
	s_waitcnt vmcnt(8)
	v_add_u32_e32 v18, v18, v7
	s_waitcnt vmcnt(7)
	v_add_u32_e32 v18, v18, v8
	s_waitcnt vmcnt(6)
	v_add_u32_e32 v18, v18, v9
	s_waitcnt vmcnt(5)
	v_add_u32_e32 v18, v18, v10
	s_waitcnt vmcnt(4)
	v_add_u32_e32 v18, v18, v11
	s_waitcnt vmcnt(3)
	v_add_u32_e32 v18, v18, v12
	s_waitcnt vmcnt(2)
	v_add_u32_e32 v18, v18, v13
	s_waitcnt vmcnt(1)
	v_add_u32_e32 v18, v18, v14
	s_waitcnt vmcnt(0)
	v_add_u32_e32 v18, v18, v15
	v_cmp_eq_u32_e32 vcc, s3, v18
	s_cbranch_vccnz .LBB0_1098
	s_and_b32 s44, s50, 0xff
	s_cmp_eq_u32 s44, 0
	s_mov_b64 s[44:45], -1
	s_mov_b64 s[48:49], -1
	s_cbranch_scc0 .LBB0_1103
	global_load_dword v18, v17, s[4:5] sc1
	s_waitcnt vmcnt(0)
	v_cmp_eq_u32_e32 vcc, 0, v18
	s_cbranch_vccnz .LBB0_1105
	s_mov_b64 s[48:49], 0

.LBB0_1115:
	s_and_b32 s22, s3, 0xff
	s_mov_b64 s[18:19], -1
	s_cmp_lg_u32 s22, 0
	s_mov_b64 s[24:25], -1
	s_cbranch_scc1 .LBB0_1118
	global_load_dword v3, v1, s[10:11] sc1
	s_waitcnt vmcnt(0)
	v_cmp_eq_u32_e32 vcc, 0, v3
	s_cbranch_vccnz .LBB0_1120
	s_mov_b64 s[24:25], 0
	s_mov_b64 s[22:23], -1

.LBB0_1132:
	s_and_b32 s18, s3, 0xff
	s_cmp_lg_u32 s18, 0
	s_mov_b64 s[22:23], -1
	s_cbranch_scc1 .LBB0_1135
	global_load_dword v2, v1, s[10:11] sc1
	s_waitcnt vmcnt(0)
	v_cmp_eq_u32_e32 vcc, 0, v2
	s_cbranch_vccnz .LBB0_1137
	s_mov_b64 s[22:23], 0
	s_mov_b64 s[18:19], -1

.LBB0_1194:
	global_load_dword v0, v147, s[26:27] sc1
	s_mov_b64 s[28:29], -1
	s_waitcnt vmcnt(0)
	v_cmp_lt_u32_e32 vcc, 3, v0
	s_cbranch_vccnz .LBB0_1193
	global_load_dword v0, v147, s[26:27] sc1
	s_waitcnt vmcnt(0)
	v_cmp_gt_u32_e32 vcc, 4, v0
	s_cbranch_vccz .LBB0_1193
	global_load_dword v0, v147, s[26:27] sc1
	s_waitcnt vmcnt(0)
	v_cmp_gt_u32_e32 vcc, 4, v0
	s_cbranch_vccz .LBB0_1193
	global_load_dword v0, v147, s[26:27] sc1
	s_waitcnt vmcnt(0)
	v_cmp_gt_u32_e32 vcc, 4, v0
	s_cbranch_vccz .LBB0_1193
	global_load_dword v0, v147, s[26:27] sc1
	s_waitcnt vmcnt(0)
	v_cmp_gt_u32_e32 vcc, 4, v0
	s_cbranch_vccz .LBB0_1193
	s_add_i32 s23, s23, -5
	s_cmp_eq_u32 s23, 0
	s_cselect_b64 s[28:29], -1, 0
	s_branch .LBB0_1193
